# LRU bwd gate segment: all A fragments and r-gate weights prefetched with counted waits, i-gate weights double-buffered, gate math stage-by-stage (on top of ping-pong LRU)
# speedup vs baseline: 1.0030x; 1.0030x over previous
; #define LAS __attribute__((address_space(3)))
; template <int dir>
; __device__ __forceinline__ void lru_pass(LAS unsigned char* lds, const Params& P, int b, int h, int q, bool dry) {
;     ...
;             { const int sl = 32 * wid + s_i; const int tlA = dir == 0 ? sl : 255 - sl;
;               const LAS unsigned char* ap = XC + tlA * XC_PITCH + 16 * g;
;               const LAS unsigned char* wrp = WB + nl * XC_PITCH + 16 * g; const LAS unsigned char* wip = wrp + 32 * XC_PITCH;
; #pragma unroll
;               for (int ks = 0; ks < 8; ++ks) { const bf16x8 A = *(const LAS bf16x8*)(ap + 32 * ks);
;                   const bf16x8 Br = *(const LAS bf16x8*)(wrp + 32 * ks), Bi = *(const LAS bf16x8*)(wip + 32 * ks);
;                   zr = __builtin_amdgcn_mfma_f32_32x32x16_bf16(A, Br, zr, 0, 0, 0); zi = __builtin_amdgcn_mfma_f32_32x32x16_bf16(A, Bi, zi, 0, 0, 0); } }
;             unsigned xcb[16], pk[16];
; #pragma unroll
;             for (int v = 0; v < 16; ++v) { const int s = sbase + v; const int tl = dir == 0 ? s : 255 - s; xcb[v] = *(const LAS bf16_t*)(XC + tl * XC_PITCH + chl * 2);
;                 if (dir == 0) pk[v] = *(const LAS bf16_t*)(TIN + tl * IO_NP + nl * 2); else pk[v] = *(const LAS unsigned*)(TIN + tl * IO_WP + nl * 4); }
;             float Pp = 1.f, E = 0.f;
; #pragma unroll
;             for (int v = 0; v < 16; ++v) {
;                 const float xcv = __uint_as_float(xcb[v] << 16);
;                 const float r = __builtin_amdgcn_rcpf(1.0f + __builtin_amdgcn_exp2f(zr[v]));
;                 const float ig = __builtin_amdgcn_rcpf(1.0f + __builtin_amdgcn_exp2f(zi[v]));
;                 const float a = __builtin_amdgcn_exp2f(cl * r);
;                 const float sq = __builtin_amdgcn_sqrtf(fmaf(-a, a, 1.0f));
;                 const float u = sq * ig * xcv;
;                 E = fmaf(a, E, u); Pp *= a; zr[v] = E; zi[v] = Pp; }
.LBB0_311:
	ds_read_b128 v[128:131], v172
	ds_read_b128 v[48:51], v173
	ds_read_b128 v[132:135], v172 offset:32
	ds_read_b128 v[52:55], v173 offset:32
	ds_read_b128 v[224:227], v172 offset:64
	ds_read_b128 v[56:59], v173 offset:64
	ds_read_b128 v[228:231], v172 offset:96
	ds_read_b128 v[60:63], v173 offset:96
	ds_read_b128 v[232:235], v172 offset:128
	ds_read_b128 v[236:239], v172 offset:160
	ds_read_b128 v[240:243], v172 offset:192
	ds_read_b128 v[244:247], v172 offset:224
	ds_read_b128 v[248:251], v173 offset:8704
	ds_read_b128 v[146:149], v173 offset:8736
	s_waitcnt lgkmcnt(12)
	v_mfma_f32_32x32x16_bf16 v[32:47], v[128:131], v[48:51], v[0:15]
	ds_read_b128 v[48:51], v173 offset:128
	s_waitcnt lgkmcnt(11)
	v_mfma_f32_32x32x16_bf16 v[32:47], v[132:135], v[52:55], v[32:47]
	ds_read_b128 v[52:55], v173 offset:160
	s_waitcnt lgkmcnt(10)
	v_mfma_f32_32x32x16_bf16 v[32:47], v[224:227], v[56:59], v[32:47]
	ds_read_b128 v[56:59], v173 offset:192
	s_waitcnt lgkmcnt(9)
	v_mfma_f32_32x32x16_bf16 v[32:47], v[228:231], v[60:63], v[32:47]
	ds_read_b128 v[60:63], v173 offset:224
	s_waitcnt lgkmcnt(3)
	v_mfma_f32_32x32x16_bf16 v[32:47], v[232:235], v[48:51], v[32:47]
	s_waitcnt lgkmcnt(2)
	v_mfma_f32_32x32x16_bf16 v[32:47], v[236:239], v[52:55], v[32:47]
	s_waitcnt lgkmcnt(1)
	v_mfma_f32_32x32x16_bf16 v[32:47], v[240:243], v[56:59], v[32:47]
	s_waitcnt lgkmcnt(0)
	v_mfma_f32_32x32x16_bf16 v[32:47], v[244:247], v[60:63], v[32:47]
	v_mfma_f32_32x32x16_bf16 v[48:63], v[128:131], v[248:251], v[16:31]
	ds_read_b128 v[128:131], v173 offset:8768
	s_nop 9
	v_exp_f32_e32 v32, v32
	v_exp_f32_e32 v33, v33
	v_exp_f32_e32 v34, v34
	v_exp_f32_e32 v35, v35
	v_exp_f32_e32 v36, v36
	v_exp_f32_e32 v37, v37
	v_exp_f32_e32 v38, v38
	v_exp_f32_e32 v39, v39
	v_exp_f32_e32 v40, v40
	v_exp_f32_e32 v41, v41
	v_mfma_f32_32x32x16_bf16 v[48:63], v[132:135], v[146:149], v[48:63]
	ds_read_b128 v[132:135], v173 offset:8800
	v_exp_f32_e32 v42, v42
	v_exp_f32_e32 v43, v43
	v_exp_f32_e32 v44, v44
	v_exp_f32_e32 v45, v45
	v_exp_f32_e32 v46, v46
	v_exp_f32_e32 v47, v47
	v_add_f32_e32 v32, 1.0, v32
	v_add_f32_e32 v33, 1.0, v33
	v_add_f32_e32 v34, 1.0, v34
	v_add_f32_e32 v35, 1.0, v35
	v_add_f32_e32 v36, 1.0, v36
	s_waitcnt lgkmcnt(1)
	v_mfma_f32_32x32x16_bf16 v[48:63], v[224:227], v[128:131], v[48:63]
	ds_read_b128 v[224:227], v173 offset:8832
	v_add_f32_e32 v37, 1.0, v37
	v_add_f32_e32 v38, 1.0, v38
	v_add_f32_e32 v39, 1.0, v39
	v_add_f32_e32 v40, 1.0, v40
	v_add_f32_e32 v41, 1.0, v41
	v_add_f32_e32 v42, 1.0, v42
	v_add_f32_e32 v43, 1.0, v43
	v_add_f32_e32 v44, 1.0, v44
	v_add_f32_e32 v45, 1.0, v45
	v_add_f32_e32 v46, 1.0, v46
	v_add_f32_e32 v47, 1.0, v47
	s_waitcnt lgkmcnt(1)
	v_mfma_f32_32x32x16_bf16 v[48:63], v[228:231], v[132:135], v[48:63]
	ds_read_b128 v[228:231], v173 offset:8864
	v_rcp_f32_e32 v32, v32
	v_rcp_f32_e32 v33, v33
	v_rcp_f32_e32 v34, v34
	v_rcp_f32_e32 v35, v35
	v_rcp_f32_e32 v36, v36
	v_rcp_f32_e32 v37, v37
	v_rcp_f32_e32 v38, v38
	v_rcp_f32_e32 v39, v39
	v_rcp_f32_e32 v40, v40
	v_rcp_f32_e32 v41, v41
	v_rcp_f32_e32 v42, v42
	s_waitcnt lgkmcnt(1)
	v_mfma_f32_32x32x16_bf16 v[48:63], v[232:235], v[224:227], v[48:63]
	ds_read_b128 v[128:131], v173 offset:8896
	v_rcp_f32_e32 v43, v43
	v_rcp_f32_e32 v44, v44
	v_rcp_f32_e32 v45, v45
	v_rcp_f32_e32 v46, v46
	v_rcp_f32_e32 v47, v47
	v_mul_f32_e32 v32, v159, v32
	v_mul_f32_e32 v33, v159, v33
	v_mul_f32_e32 v34, v159, v34
	v_mul_f32_e32 v35, v159, v35
	v_mul_f32_e32 v36, v159, v36
	v_mul_f32_e32 v37, v159, v37
	s_waitcnt lgkmcnt(1)
	v_mfma_f32_32x32x16_bf16 v[48:63], v[236:239], v[228:231], v[48:63]
	ds_read_b128 v[132:135], v173 offset:8928
	v_mul_f32_e32 v38, v159, v38
	v_mul_f32_e32 v39, v159, v39
	v_mul_f32_e32 v40, v159, v40
	v_mul_f32_e32 v41, v159, v41
	v_mul_f32_e32 v42, v159, v42
	v_mul_f32_e32 v43, v159, v43
	v_mul_f32_e32 v44, v159, v44
	v_mul_f32_e32 v45, v159, v45
	v_mul_f32_e32 v46, v159, v46
	v_mul_f32_e32 v47, v159, v47
	v_exp_f32_e32 v32, v32
	s_waitcnt lgkmcnt(1)
	v_mfma_f32_32x32x16_bf16 v[48:63], v[240:243], v[128:131], v[48:63]
	v_exp_f32_e32 v33, v33
	v_exp_f32_e32 v34, v34
	v_exp_f32_e32 v35, v35
	v_exp_f32_e32 v36, v36
	v_exp_f32_e32 v37, v37
	v_exp_f32_e32 v38, v38
	v_exp_f32_e32 v39, v39
	v_exp_f32_e32 v40, v40
	v_exp_f32_e32 v41, v41
	v_exp_f32_e32 v42, v42
	v_exp_f32_e32 v43, v43
	s_waitcnt lgkmcnt(0)
	v_mfma_f32_32x32x16_bf16 v[48:63], v[244:247], v[132:135], v[48:63]
	v_exp_f32_e32 v44, v44
	v_exp_f32_e32 v45, v45
	v_exp_f32_e32 v46, v46
	v_exp_f32_e32 v47, v47
	ds_read_u16 v162, v174
	ds_read_b32 v226, v175
	ds_read_u16 v163, v176
	ds_read_b32 v225, v177
	ds_read_u16 v232, v178
	ds_read_b32 v224, v179
	ds_read_u16 v233, v180
	ds_read_b32 v223, v181
	ds_read_u16 v234, v182
	ds_read_b32 v135, v183
	ds_read_u16 v235, v184
	ds_read_b32 v134, v185
	ds_read_u16 v236, v186
	ds_read_b32 v133, v187
	ds_read_u16 v237, v188
	ds_read_b32 v131, v189
	ds_read_u16 v146, v190
	ds_read_b32 v132, v191
	ds_read_u16 v147, v192
	ds_read_b32 v130, v193
	ds_read_u16 v148, v194
	ds_read_b32 v129, v195
	ds_read_u16 v149, v196
	ds_read_b32 v128, v197
	ds_read_u16 v239, v198
	ds_read_b32 v67, v199
	ds_read_u16 v240, v200
	ds_read_b32 v66, v201
	ds_read_u16 v241, v202
	ds_read_b32 v64, v203
	ds_read_u16 v242, v204
	ds_read_b32 v251, v205
	v_exp_f32_e32 v48, v48
	v_exp_f32_e32 v49, v49
	v_exp_f32_e32 v50, v50
	v_exp_f32_e32 v51, v51
	v_exp_f32_e32 v52, v52
	v_exp_f32_e32 v53, v53
	v_exp_f32_e32 v54, v54
	v_exp_f32_e32 v55, v55
	v_exp_f32_e32 v56, v56
	v_exp_f32_e32 v57, v57
	v_exp_f32_e32 v58, v58
	v_exp_f32_e32 v59, v59
	v_exp_f32_e32 v60, v60
	v_exp_f32_e32 v61, v61
	v_exp_f32_e32 v62, v62
	v_exp_f32_e32 v63, v63
	v_add_f32_e32 v48, 1.0, v48
	v_add_f32_e32 v49, 1.0, v49
	v_add_f32_e32 v50, 1.0, v50
	v_add_f32_e32 v51, 1.0, v51
	v_add_f32_e32 v52, 1.0, v52
	v_add_f32_e32 v53, 1.0, v53
	v_add_f32_e32 v54, 1.0, v54
	v_add_f32_e32 v55, 1.0, v55
	v_add_f32_e32 v56, 1.0, v56
	v_add_f32_e32 v57, 1.0, v57
	v_add_f32_e32 v58, 1.0, v58
	v_add_f32_e32 v59, 1.0, v59
	v_add_f32_e32 v60, 1.0, v60
	v_add_f32_e32 v61, 1.0, v61
	v_add_f32_e32 v62, 1.0, v62
	v_add_f32_e32 v63, 1.0, v63
	v_rcp_f32_e32 v48, v48
	v_rcp_f32_e32 v49, v49
	v_rcp_f32_e32 v50, v50
	v_rcp_f32_e32 v51, v51
	v_rcp_f32_e32 v52, v52
	v_rcp_f32_e32 v53, v53
	v_rcp_f32_e32 v54, v54
	v_rcp_f32_e32 v55, v55
	v_rcp_f32_e32 v56, v56
	v_rcp_f32_e32 v57, v57
	v_rcp_f32_e32 v58, v58
	v_rcp_f32_e32 v59, v59
	v_rcp_f32_e32 v60, v60
	v_rcp_f32_e32 v61, v61
	v_rcp_f32_e32 v62, v62
	v_rcp_f32_e32 v63, v63
	s_waitcnt lgkmcnt(0)
; template <int dir>
; __device__ __forceinline__ void lru_pass(LAS unsigned char* lds, const Params& P, int b, int h, int q, bool dry) {
;     ...
;             float Pp = 1.f, E = 0.f;
; #pragma unroll
;             for (int v = 0; v < 16; ++v) {
;                 const float xcv = __uint_as_float(xcb[v] << 16);
;                 const float r = __builtin_amdgcn_rcpf(1.0f + __builtin_amdgcn_exp2f(zr[v]));
;                 const float ig = __builtin_amdgcn_rcpf(1.0f + __builtin_amdgcn_exp2f(zi[v]));
;                 const float a = __builtin_amdgcn_exp2f(cl * r);
;                 const float sq = __builtin_amdgcn_sqrtf(fmaf(-a, a, 1.0f));
;                 const float u = sq * ig * xcv;
;                 E = fmaf(a, E, u); Pp *= a; zr[v] = E; zi[v] = Pp; }
;             const float Po = __shfl_xor(Pp, 32), Eo = __shfl_xor(E, 32);
;             const float P0 = g ? Po : Pp, E0 = g ? Eo : E, P1 = g ? Pp : Po, E1 = g ? E : Eo;
;             if (g == 0) { AGG[(wid * 2 + 0) * 32 + nl] = P0 * P1; AGG[(wid * 2 + 1) * 32 + nl] = fmaf(P1, E0, E1); }
	v_fma_f32 v244, -v32, v32, 1.0
	v_fma_f32 v245, -v33, v33, 1.0
	v_fma_f32 v246, -v34, v34, 1.0
	v_fma_f32 v247, -v35, v35, 1.0
	v_sqrt_f32_e32 v244, v244
	v_sqrt_f32_e32 v245, v245
	v_sqrt_f32_e32 v246, v246
	v_sqrt_f32_e32 v247, v247
	v_lshlrev_b32_e32 v162, 16, v162
	v_lshlrev_b32_e32 v163, 16, v163
	v_lshlrev_b32_e32 v232, 16, v232
	v_lshlrev_b32_e32 v233, 16, v233
	v_mul_f32_e32 v244, v244, v48
	v_mul_f32_e32 v245, v245, v49
	v_mul_f32_e32 v246, v246, v50
	v_mul_f32_e32 v247, v247, v51
	v_mul_f32_e32 v49, v244, v162
	v_mul_f32_e32 v228, v245, v163
	v_mul_f32_e32 v229, v246, v232
	v_mul_f32_e32 v230, v247, v233
	v_fma_f32 v244, -v36, v36, 1.0
	v_fma_f32 v245, -v37, v37, 1.0
	v_fma_f32 v246, -v38, v38, 1.0
	v_fma_f32 v247, -v39, v39, 1.0
	v_sqrt_f32_e32 v244, v244
	v_sqrt_f32_e32 v245, v245
	v_sqrt_f32_e32 v246, v246
	v_sqrt_f32_e32 v247, v247
	v_lshlrev_b32_e32 v234, 16, v234
	v_lshlrev_b32_e32 v235, 16, v235
	v_lshlrev_b32_e32 v236, 16, v236
	v_lshlrev_b32_e32 v237, 16, v237
	v_mul_f32_e32 v244, v244, v52
	v_mul_f32_e32 v245, v245, v53
	v_mul_f32_e32 v246, v246, v54
	v_mul_f32_e32 v247, v247, v55
	v_mul_f32_e32 v231, v244, v234
	v_mul_f32_e32 v232, v245, v235
	v_mul_f32_e32 v233, v246, v236
	v_mul_f32_e32 v234, v247, v237
	v_fma_f32 v244, -v40, v40, 1.0
	v_fma_f32 v245, -v41, v41, 1.0
	v_fma_f32 v246, -v42, v42, 1.0
	v_fma_f32 v247, -v43, v43, 1.0
	v_sqrt_f32_e32 v244, v244
	v_sqrt_f32_e32 v245, v245
	v_sqrt_f32_e32 v246, v246
	v_sqrt_f32_e32 v247, v247
	v_lshlrev_b32_e32 v146, 16, v146
	v_lshlrev_b32_e32 v147, 16, v147
	v_lshlrev_b32_e32 v148, 16, v148
	v_lshlrev_b32_e32 v149, 16, v149
	v_mul_f32_e32 v244, v244, v56
	v_mul_f32_e32 v245, v245, v57
	v_mul_f32_e32 v246, v246, v58
	v_mul_f32_e32 v247, v247, v59
	v_mul_f32_e32 v235, v244, v146
	v_mul_f32_e32 v236, v245, v147
	v_mul_f32_e32 v237, v246, v148
	v_mul_f32_e32 v238, v247, v149
	v_fma_f32 v244, -v44, v44, 1.0
	v_fma_f32 v245, -v45, v45, 1.0
	v_fma_f32 v246, -v46, v46, 1.0
	v_fma_f32 v247, -v47, v47, 1.0
	v_sqrt_f32_e32 v244, v244
	v_sqrt_f32_e32 v245, v245
	v_sqrt_f32_e32 v246, v246
	v_sqrt_f32_e32 v247, v247
	v_lshlrev_b32_e32 v239, 16, v239
	v_lshlrev_b32_e32 v240, 16, v240
	v_lshlrev_b32_e32 v241, 16, v241
	v_lshlrev_b32_e32 v242, 16, v242
	v_mul_f32_e32 v244, v244, v60
	v_mul_f32_e32 v245, v245, v61
	v_mul_f32_e32 v246, v246, v62
	v_mul_f32_e32 v247, v247, v63
	v_mul_f32_e32 v239, v244, v239
	v_mul_f32_e32 v240, v245, v240
	v_mul_f32_e32 v63, v246, v241
	v_mul_f32_e32 v241, v247, v242
	v_mov_b32_e32 v227, v32
	v_fmac_f32_e32 v49, 0, v32
	v_fmac_f32_e32 v228, v33, v49
	v_mul_f32_e32 v50, v227, v33
	v_fmac_f32_e32 v229, v34, v228
	v_mul_f32_e32 v51, v50, v34
	v_fmac_f32_e32 v230, v35, v229
	v_mul_f32_e32 v52, v51, v35
	v_fmac_f32_e32 v231, v36, v230
	v_mul_f32_e32 v53, v52, v36
	v_fmac_f32_e32 v232, v37, v231
	v_mul_f32_e32 v54, v53, v37
	v_fmac_f32_e32 v233, v38, v232
	v_mul_f32_e32 v55, v54, v38
	v_fmac_f32_e32 v234, v39, v233
	v_mul_f32_e32 v56, v55, v39
	v_fmac_f32_e32 v235, v40, v234
	v_mul_f32_e32 v57, v56, v40
	v_fmac_f32_e32 v236, v41, v235
	v_mul_f32_e32 v58, v57, v41
	v_fmac_f32_e32 v237, v42, v236
	v_mul_f32_e32 v59, v58, v42
	v_fmac_f32_e32 v238, v43, v237
	v_mul_f32_e32 v60, v59, v43
	v_fmac_f32_e32 v239, v44, v238
	v_mul_f32_e32 v61, v60, v44
	v_fmac_f32_e32 v240, v45, v239
	v_mul_f32_e32 v62, v61, v45
	v_fmac_f32_e32 v63, v46, v240
	v_mul_f32_e32 v243, v62, v46
	v_fmac_f32_e32 v241, v47, v63
	v_mul_f32_e32 v242, v243, v47
	ds_bpermute_b32 v244, v157, v242
	ds_bpermute_b32 v245, v157, v241
	s_and_saveexec_b64 s[18:19], vcc
	s_cbranch_execz .LBB0_313
	s_waitcnt lgkmcnt(0)
	v_fma_f32 v32, v244, v241, v245
	v_mul_f32_e32 v33, v242, v244
	v_add_u32_e32 v35, s98, v254
	ds_write2_b32 v35, v33, v32 offset1:32
; #define LAS __attribute__((address_space(3)))
; __device__ __forceinline__ unsigned cvt_pk_bf16(float lo, float hi) { unsigned r; asm volatile("v_cvt_pk_bf16_f32 %0, %1, %2" : "=v"(r) : "v"(lo), "v"(hi)); return r; }
; __device__ __forceinline__ float bf_lo(unsigned u) { return __uint_as_float(u << 16); }
; __device__ __forceinline__ float bf_hi(unsigned u) { return __uint_as_float(u & 0xffff0000u); }
; __device__ __forceinline__ bf16_t f2bf(float f) { return (bf16_t)(cvt_pk_bf16(f, 0.f) & 0xffffu); }
; #define LDS_BARRIER() do { asm volatile("s_waitcnt lgkmcnt(0)" ::: "memory"); __builtin_amdgcn_s_barrier(); asm volatile("" ::: "memory"); } while (0)
; template <int dir>
; __device__ __forceinline__ void lru_pass(LAS unsigned char* lds, const Params& P, int b, int h, int q, bool dry) {
;     ...
;             LDS_BARRIER();
;             float cin = carry, cend = carry;
; #pragma unroll
;             for (int w = 0; w < 8; ++w) { const float pw = AGG[(w * 2 + 0) * 32 + nl], ew = AGG[(w * 2 + 1) * 32 + nl]; if (w == wid) cin = cend; cend = fmaf(pw, cend, ew); }
;             carry = cend;
;             if (g) cin = fmaf(P0, cin, E0);
;             if (!isctx) {
; #pragma unroll
;                 for (int v = 0; v < 16; ++v) { const float hv = fmaf(zi[v], cin, zr[v]);
;                     const int s = sbase + v; const int tl = dir == 0 ? s : 255 - s;
;                     if (dir == 0) *(LAS unsigned*)(TOUT + tl * IO_WP + nl * 4) = (cvt_pk_bf16(hv, 0.f) & 0xffffu) | (pk[v] << 16);
;                     else *(LAS bf16_t*)(TOUT + tl * IO_NP + nl * 2) = f2bf((bf_lo(pk[v]) + hv) * bf_hi(pk[v])); }
.LBB0_313:
	s_or_b64 exec, exec, s[18:19]
	s_waitcnt lgkmcnt(0)
	s_barrier
	v_add_u32_e32 v34, s99, v161
	ds_read2_b32 v[36:37], v34 offset1:32
	ds_read2_b32 v[38:39], v34 offset0:64 offset1:96
	ds_read2_b32 v[40:41], v34 offset0:128 offset1:160
	ds_read2_b32 v[42:43], v34 offset0:192 offset1:224
	v_add_u32_e32 v32, s100, v161
	s_waitcnt lgkmcnt(3)
	v_fmac_f32_e32 v37, v36, v222
	s_waitcnt lgkmcnt(2)
	v_fmac_f32_e32 v39, v38, v37
	s_waitcnt lgkmcnt(1)
	v_fmac_f32_e32 v41, v40, v39
	ds_read2_b32 v[44:45], v32 offset1:32
	ds_read2_b32 v[46:47], v32 offset0:64 offset1:96
	ds_read2_b32 v[34:35], v32 offset0:128 offset1:160
	ds_read2_b32 v[32:33], v32 offset0:192 offset1:224
	s_waitcnt lgkmcnt(4)
	v_fmac_f32_e32 v43, v42, v41
	s_waitcnt lgkmcnt(3)
	v_fmac_f32_e32 v45, v44, v43
	s_waitcnt lgkmcnt(2)
	v_fmac_f32_e32 v47, v46, v45
	s_cmp_eq_u32 s44, 0
	s_waitcnt lgkmcnt(1)
	v_fmac_f32_e32 v35, v34, v47
	s_cbranch_scc1 .LBB0_315
	v_cndmask_b32_e64 v37, v222, v37, s[14:15]
	v_cndmask_b32_e64 v37, v37, v39, s[12:13]
	v_cndmask_b32_e64 v37, v37, v41, s[10:11]
	v_cndmask_b32_e64 v37, v37, v43, s[8:9]
	v_cndmask_b32_e64 v37, v37, v45, s[4:5]
	v_cndmask_b32_e64 v37, v37, v47, s[16:17]
	v_cndmask_b32_e32 v34, v244, v242, vcc
	v_cndmask_b32_e32 v36, v245, v241, vcc
	v_cndmask_b32_e64 v37, v37, v35, s[0:1]
	v_fmac_f32_e32 v36, v34, v37
	v_cndmask_b32_e32 v34, v36, v37, vcc
	v_fmac_f32_e32 v49, v227, v34
	v_lshlrev_b32_e32 v36, 16, v226
	v_add_f32_e32 v36, v49, v36
	v_and_b32_e32 v37, 0xffff0000, v226
	v_mul_f32_e32 v36, v36, v37
	v_cvt_pk_bf16_f32 v36, v36, v65
	ds_write_b16 v206, v36
	v_fmac_f32_e32 v228, v50, v34
	v_lshlrev_b32_e32 v36, 16, v225
	v_add_f32_e32 v36, v228, v36
	v_and_b32_e32 v37, 0xffff0000, v225
	v_mul_f32_e32 v36, v36, v37
	v_cvt_pk_bf16_f32 v36, v36, v65
	ds_write_b16 v207, v36
	v_fmac_f32_e32 v229, v51, v34
	v_lshlrev_b32_e32 v36, 16, v224
	v_add_f32_e32 v36, v229, v36
	v_and_b32_e32 v37, 0xffff0000, v224
	v_mul_f32_e32 v36, v36, v37
	v_cvt_pk_bf16_f32 v36, v36, v65
	ds_write_b16 v208, v36
	v_fmac_f32_e32 v230, v52, v34
	v_lshlrev_b32_e32 v36, 16, v223
	v_add_f32_e32 v36, v230, v36
	v_and_b32_e32 v37, 0xffff0000, v223
	v_mul_f32_e32 v36, v36, v37
	v_cvt_pk_bf16_f32 v36, v36, v65
	ds_write_b16 v209, v36
	v_fmac_f32_e32 v231, v53, v34
	v_lshlrev_b32_e32 v36, 16, v135
	v_add_f32_e32 v36, v231, v36
	v_and_b32_e32 v37, 0xffff0000, v135
	v_mul_f32_e32 v36, v36, v37
	v_cvt_pk_bf16_f32 v36, v36, v65
	ds_write_b16 v210, v36
	v_fmac_f32_e32 v232, v54, v34
	v_lshlrev_b32_e32 v36, 16, v134
	v_add_f32_e32 v36, v232, v36
	v_and_b32_e32 v37, 0xffff0000, v134
	v_mul_f32_e32 v36, v36, v37
	v_cvt_pk_bf16_f32 v36, v36, v65
	ds_write_b16 v211, v36
	v_fmac_f32_e32 v233, v55, v34
	v_lshlrev_b32_e32 v36, 16, v133
	v_add_f32_e32 v36, v233, v36
	v_and_b32_e32 v37, 0xffff0000, v133
	v_mul_f32_e32 v36, v36, v37
	v_cvt_pk_bf16_f32 v36, v36, v65
	ds_write_b16 v212, v36
	v_fmac_f32_e32 v234, v56, v34
	v_lshlrev_b32_e32 v36, 16, v131
	v_add_f32_e32 v36, v234, v36
	v_and_b32_e32 v37, 0xffff0000, v131
	v_mul_f32_e32 v36, v36, v37
	v_cvt_pk_bf16_f32 v36, v36, v65
	ds_write_b16 v213, v36
	v_fmac_f32_e32 v235, v57, v34
	v_lshlrev_b32_e32 v36, 16, v132
	v_add_f32_e32 v36, v235, v36
	v_and_b32_e32 v37, 0xffff0000, v132
	v_mul_f32_e32 v36, v36, v37
	v_cvt_pk_bf16_f32 v36, v36, v65
	ds_write_b16 v214, v36
	v_fmac_f32_e32 v236, v58, v34
	v_lshlrev_b32_e32 v36, 16, v130
	v_add_f32_e32 v36, v236, v36
	v_and_b32_e32 v37, 0xffff0000, v130
	v_mul_f32_e32 v36, v36, v37
	v_cvt_pk_bf16_f32 v36, v36, v65
	ds_write_b16 v215, v36
	v_fmac_f32_e32 v237, v59, v34
	v_lshlrev_b32_e32 v36, 16, v129
	v_add_f32_e32 v36, v237, v36
	v_and_b32_e32 v37, 0xffff0000, v129
	v_mul_f32_e32 v36, v36, v37
	v_cvt_pk_bf16_f32 v36, v36, v65
	ds_write_b16 v216, v36
	v_fmac_f32_e32 v238, v60, v34
	v_lshlrev_b32_e32 v36, 16, v128
	v_add_f32_e32 v36, v238, v36
	v_and_b32_e32 v37, 0xffff0000, v128
	v_mul_f32_e32 v36, v36, v37
	v_cvt_pk_bf16_f32 v36, v36, v65
	ds_write_b16 v217, v36
	v_fmac_f32_e32 v239, v61, v34
	v_lshlrev_b32_e32 v36, 16, v67
	v_add_f32_e32 v36, v239, v36
	v_and_b32_e32 v37, 0xffff0000, v67
	v_mul_f32_e32 v36, v36, v37
	v_cvt_pk_bf16_f32 v36, v36, v65
	ds_write_b16 v218, v36
	v_fmac_f32_e32 v240, v62, v34
	v_lshlrev_b32_e32 v36, 16, v66
	v_add_f32_e32 v36, v240, v36
	v_and_b32_e32 v37, 0xffff0000, v66
	v_mul_f32_e32 v36, v36, v37
	v_cvt_pk_bf16_f32 v36, v36, v65
	ds_write_b16 v219, v36
	v_fmac_f32_e32 v63, v243, v34
	v_lshlrev_b32_e32 v36, 16, v64
	v_add_f32_e32 v36, v63, v36
	v_and_b32_e32 v37, 0xffff0000, v64
	v_mul_f32_e32 v36, v36, v37
	v_cvt_pk_bf16_f32 v36, v36, v65
	v_fmac_f32_e32 v241, v242, v34
	v_lshlrev_b32_e32 v34, 16, v251
	ds_write_b16 v220, v36
	v_add_f32_e32 v34, v241, v34
	v_and_b32_e32 v36, 0xffff0000, v251
	v_mul_f32_e32 v34, v34, v36
	v_cvt_pk_bf16_f32 v34, v34, v65
	ds_write_b16 v221, v34
